# accumulator clearing before each unit: 128 v_mov_b32 -> 64 v_mov_b64 (on the micro-edit stack)
# speedup vs baseline: 1.0042x; 1.0015x over previous
.LBB0_227:
	s_ashr_i32 s69, s68, 31
	s_lshl_b64 s[10:11], s[68:69], 19
	s_add_u32 s72, s52, s10
	s_addc_u32 s73, s53, s11
	s_and_b64 s[10:11], s[4:5], exec
	s_cselect_b32 s18, s73, s7
	s_cselect_b32 s69, s72, s6
	s_ashr_i32 s71, s70, 31
	s_lshl_b64 s[10:11], s[70:71], 19
	s_add_u32 s74, s59, s10
	s_addc_u32 s75, s67, s11
	s_and_b64 s[10:11], s[4:5], exec
	s_cselect_b32 s71, s75, s9
	s_cselect_b32 s77, s74, s8
	s_add_u32 vcc_lo, s8, 0x100
	s_addc_u32 vcc_hi, s9, 0
	s_mov_b32 s92, -2
	v_mov_b64_e32 v[0:1], 0
	v_mov_b64_e32 v[2:3], 0
	v_mov_b64_e32 v[4:5], 0
	v_mov_b64_e32 v[6:7], 0
	v_mov_b64_e32 v[8:9], 0
	v_mov_b64_e32 v[10:11], 0
	v_mov_b64_e32 v[12:13], 0
	v_mov_b64_e32 v[14:15], 0
	v_mov_b64_e32 v[16:17], 0
	v_mov_b64_e32 v[18:19], 0
	v_mov_b64_e32 v[20:21], 0
	v_mov_b64_e32 v[22:23], 0
	v_mov_b64_e32 v[24:25], 0
	v_mov_b64_e32 v[26:27], 0
	v_mov_b64_e32 v[28:29], 0
	v_mov_b64_e32 v[30:31], 0
	v_mov_b64_e32 v[32:33], 0
	v_mov_b64_e32 v[34:35], 0
	v_mov_b64_e32 v[36:37], 0
	v_mov_b64_e32 v[38:39], 0
	v_mov_b64_e32 v[40:41], 0
	v_mov_b64_e32 v[42:43], 0
	v_mov_b64_e32 v[44:45], 0
	v_mov_b64_e32 v[46:47], 0
	v_mov_b64_e32 v[48:49], 0
	v_mov_b64_e32 v[50:51], 0
	v_mov_b64_e32 v[52:53], 0
	v_mov_b64_e32 v[54:55], 0
	v_mov_b64_e32 v[56:57], 0
	v_mov_b64_e32 v[58:59], 0
	v_mov_b64_e32 v[60:61], 0
	v_mov_b64_e32 v[62:63], 0
	v_mov_b64_e32 v[64:65], 0
	v_mov_b64_e32 v[66:67], 0
	v_mov_b64_e32 v[68:69], 0
	v_mov_b64_e32 v[70:71], 0
	v_mov_b64_e32 v[72:73], 0
	v_mov_b64_e32 v[74:75], 0
	v_mov_b64_e32 v[76:77], 0
	v_mov_b64_e32 v[78:79], 0
	v_mov_b64_e32 v[80:81], 0
	v_mov_b64_e32 v[82:83], 0
	v_mov_b64_e32 v[84:85], 0
	v_mov_b64_e32 v[86:87], 0
	v_mov_b64_e32 v[88:89], 0
	v_mov_b64_e32 v[90:91], 0
	v_mov_b64_e32 v[92:93], 0
	v_mov_b64_e32 v[94:95], 0
	v_mov_b64_e32 v[96:97], 0
	v_mov_b64_e32 v[98:99], 0
	v_mov_b64_e32 v[100:101], 0
	v_mov_b64_e32 v[102:103], 0
	v_mov_b64_e32 v[104:105], 0
	v_mov_b64_e32 v[106:107], 0
	v_mov_b64_e32 v[108:109], 0
	v_mov_b64_e32 v[110:111], 0
	v_mov_b64_e32 v[112:113], 0
	v_mov_b64_e32 v[114:115], 0
	v_mov_b64_e32 v[116:117], 0
	v_mov_b64_e32 v[118:119], 0
	v_mov_b64_e32 v[120:121], 0
	v_mov_b64_e32 v[122:123], 0
	v_mov_b64_e32 v[124:125], 0
	v_mov_b64_e32 v[126:127], 0

.LBB0_506:
	s_ashr_i32 s29, s28, 31
	v_cmp_lt_i64_e32 vcc, s[38:39], v[204:205]
	s_lshl_b64 s[38:39], s[28:29], 19
	s_add_u32 s38, s14, s38
	s_addc_u32 s39, s15, s39
	s_and_b64 s[40:41], vcc, exec
	s_cselect_b32 s8, s39, s43
	s_cselect_b32 s21, s38, s42
	s_ashr_i32 s27, s26, 31
	s_lshl_b64 s[40:41], s[26:27], 19
	s_add_u32 s40, s33, s40
	s_addc_u32 s41, s34, s41
	s_and_b64 s[46:47], vcc, exec
	s_cselect_b32 s27, s41, s45
	s_cselect_b32 s29, s40, s44
	s_add_u32 s80, s44, 0x100
	s_addc_u32 s81, s45, 0
	s_mov_b32 s83, -2
	v_mov_b64_e32 v[0:1], 0
	v_mov_b64_e32 v[2:3], 0
	v_mov_b64_e32 v[4:5], 0
	v_mov_b64_e32 v[6:7], 0
	v_mov_b64_e32 v[8:9], 0
	v_mov_b64_e32 v[10:11], 0
	v_mov_b64_e32 v[12:13], 0
	v_mov_b64_e32 v[14:15], 0
	v_mov_b64_e32 v[16:17], 0
	v_mov_b64_e32 v[18:19], 0
	v_mov_b64_e32 v[20:21], 0
	v_mov_b64_e32 v[22:23], 0
	v_mov_b64_e32 v[24:25], 0
	v_mov_b64_e32 v[26:27], 0
	v_mov_b64_e32 v[28:29], 0
	v_mov_b64_e32 v[30:31], 0
	v_mov_b64_e32 v[32:33], 0
	v_mov_b64_e32 v[34:35], 0
	v_mov_b64_e32 v[36:37], 0
	v_mov_b64_e32 v[38:39], 0
	v_mov_b64_e32 v[40:41], 0
	v_mov_b64_e32 v[42:43], 0
	v_mov_b64_e32 v[44:45], 0
	v_mov_b64_e32 v[46:47], 0
	v_mov_b64_e32 v[48:49], 0
	v_mov_b64_e32 v[50:51], 0
	v_mov_b64_e32 v[52:53], 0
	v_mov_b64_e32 v[54:55], 0
	v_mov_b64_e32 v[56:57], 0
	v_mov_b64_e32 v[58:59], 0
	v_mov_b64_e32 v[60:61], 0
	v_mov_b64_e32 v[62:63], 0
	v_mov_b64_e32 v[64:65], 0
	v_mov_b64_e32 v[66:67], 0
	v_mov_b64_e32 v[68:69], 0
	v_mov_b64_e32 v[70:71], 0
	v_mov_b64_e32 v[72:73], 0
	v_mov_b64_e32 v[74:75], 0
	v_mov_b64_e32 v[76:77], 0
	v_mov_b64_e32 v[78:79], 0
	v_mov_b64_e32 v[80:81], 0
	v_mov_b64_e32 v[82:83], 0
	v_mov_b64_e32 v[84:85], 0
	v_mov_b64_e32 v[86:87], 0
	v_mov_b64_e32 v[88:89], 0
	v_mov_b64_e32 v[90:91], 0
	v_mov_b64_e32 v[92:93], 0
	v_mov_b64_e32 v[94:95], 0
	v_mov_b64_e32 v[96:97], 0
	v_mov_b64_e32 v[98:99], 0
	v_mov_b64_e32 v[100:101], 0
	v_mov_b64_e32 v[102:103], 0
	v_mov_b64_e32 v[104:105], 0
	v_mov_b64_e32 v[106:107], 0
	v_mov_b64_e32 v[108:109], 0
	v_mov_b64_e32 v[110:111], 0
	v_mov_b64_e32 v[112:113], 0
	v_mov_b64_e32 v[114:115], 0
	v_mov_b64_e32 v[116:117], 0
	v_mov_b64_e32 v[118:119], 0
	v_mov_b64_e32 v[120:121], 0
	v_mov_b64_e32 v[122:123], 0
	v_mov_b64_e32 v[124:125], 0
	v_mov_b64_e32 v[126:127], 0

.LBB0_567:
	s_ashr_i32 s19, s18, 31
	s_lshl_b64 s[20:21], s[18:19], 19
	s_add_u32 s20, s14, s20
	s_addc_u32 s21, s15, s21
	s_and_b64 s[22:23], s[4:5], exec
	s_cselect_b32 s19, s21, s29
	s_cselect_b32 s27, s20, s28
	s_ashr_i32 s17, s16, 31
	s_lshl_b64 s[22:23], s[16:17], 19
	s_add_u32 s22, s33, s22
	s_addc_u32 s23, s34, s23
	s_and_b64 s[38:39], s[4:5], exec
	s_cselect_b32 s17, s23, s37
	s_cselect_b32 s73, s22, s36
	s_add_u32 s74, s36, 0x100
	s_addc_u32 s75, s37, 0
	s_mov_b32 s76, -2
	v_mov_b64_e32 v[0:1], 0
	v_mov_b64_e32 v[2:3], 0
	v_mov_b64_e32 v[4:5], 0
	v_mov_b64_e32 v[6:7], 0
	v_mov_b64_e32 v[8:9], 0
	v_mov_b64_e32 v[10:11], 0
	v_mov_b64_e32 v[12:13], 0
	v_mov_b64_e32 v[14:15], 0
	v_mov_b64_e32 v[16:17], 0
	v_mov_b64_e32 v[18:19], 0
	v_mov_b64_e32 v[20:21], 0
	v_mov_b64_e32 v[22:23], 0
	v_mov_b64_e32 v[24:25], 0
	v_mov_b64_e32 v[26:27], 0
	v_mov_b64_e32 v[28:29], 0
	v_mov_b64_e32 v[30:31], 0
	v_mov_b64_e32 v[32:33], 0
	v_mov_b64_e32 v[34:35], 0
	v_mov_b64_e32 v[36:37], 0
	v_mov_b64_e32 v[38:39], 0
	v_mov_b64_e32 v[40:41], 0
	v_mov_b64_e32 v[42:43], 0
	v_mov_b64_e32 v[44:45], 0
	v_mov_b64_e32 v[46:47], 0
	v_mov_b64_e32 v[48:49], 0
	v_mov_b64_e32 v[50:51], 0
	v_mov_b64_e32 v[52:53], 0
	v_mov_b64_e32 v[54:55], 0
	v_mov_b64_e32 v[56:57], 0
	v_mov_b64_e32 v[58:59], 0
	v_mov_b64_e32 v[60:61], 0
	v_mov_b64_e32 v[62:63], 0
	v_mov_b64_e32 v[64:65], 0
	v_mov_b64_e32 v[66:67], 0
	v_mov_b64_e32 v[68:69], 0
	v_mov_b64_e32 v[70:71], 0
	v_mov_b64_e32 v[72:73], 0
	v_mov_b64_e32 v[74:75], 0
	v_mov_b64_e32 v[76:77], 0
	v_mov_b64_e32 v[78:79], 0
	v_mov_b64_e32 v[80:81], 0
	v_mov_b64_e32 v[82:83], 0
	v_mov_b64_e32 v[84:85], 0
	v_mov_b64_e32 v[86:87], 0
	v_mov_b64_e32 v[88:89], 0
	v_mov_b64_e32 v[90:91], 0
	v_mov_b64_e32 v[92:93], 0
	v_mov_b64_e32 v[94:95], 0
	v_mov_b64_e32 v[96:97], 0
	v_mov_b64_e32 v[98:99], 0
	v_mov_b64_e32 v[100:101], 0
	v_mov_b64_e32 v[102:103], 0
	v_mov_b64_e32 v[104:105], 0
	v_mov_b64_e32 v[106:107], 0
	v_mov_b64_e32 v[108:109], 0
	v_mov_b64_e32 v[110:111], 0
	v_mov_b64_e32 v[112:113], 0
	v_mov_b64_e32 v[114:115], 0
	v_mov_b64_e32 v[116:117], 0
	v_mov_b64_e32 v[118:119], 0
	v_mov_b64_e32 v[120:121], 0
	v_mov_b64_e32 v[122:123], 0
	v_mov_b64_e32 v[124:125], 0
	v_mov_b64_e32 v[126:127], 0

.LBB0_615:
	v_add_u32_e32 v151, s51, v149
	ds_read_b128 v[152:155], v151
	ds_read_b128 v[156:159], v151 offset:1024
	ds_read_b128 v[160:163], v151 offset:2048
	ds_read_b128 v[164:167], v151 offset:3072
	v_add_u32_e32 v151, s56, v149
	ds_read_b128 v[168:171], v151
	ds_read_b128 v[172:175], v151 offset:1024
	ds_read_b128 v[176:179], v151 offset:2048
	ds_read_b128 v[180:183], v151 offset:3072
	s_add_u32 s38, s12, s36
	s_addc_u32 s39, s13, s37
	s_cmp_eq_u32 s63, 60
	s_cselect_b32 s42, s59, s38
	s_cselect_b32 s43, s23, s39
	s_cselect_b32 s40, s60, s61
	s_cselect_b32 s41, s21, s62
	s_add_u32 s38, s42, 0x8000
	s_addc_u32 s39, s43, 0
	s_add_i32 m0, s44, 0xc000
	ds_read_b128 v[184:187], v150
	ds_read_b128 v[188:191], v150 offset:1024
	ds_read_b128 v[192:195], v150 offset:2048
	ds_read_b128 v[196:199], v150 offset:3072
	ds_read_b128 v[200:203], v150 offset:4096
	ds_read_b128 v[204:207], v150 offset:5120
	ds_read_b128 v[208:211], v150 offset:6144
	ds_read_b128 v[212:215], v150 offset:7168
	global_load_lds_dwordx4 v146, s[12:13]
	s_add_i32 m0, s44, 0xe000
	s_nop 0
	global_load_lds_dwordx4 v144, s[12:13]
	s_waitcnt vmcnt(8)
	s_waitcnt lgkmcnt(0)
	s_setprio 1
	s_barrier
	v_mfma_f32_16x16x32_bf16 v[124:127], v[152:155], v[184:187], v[124:127]
	v_mfma_f32_16x16x32_bf16 v[120:123], v[160:163], v[184:187], v[120:123]
	v_mfma_f32_16x16x32_bf16 v[108:111], v[152:155], v[192:195], v[108:111]
	v_mfma_f32_16x16x32_bf16 v[104:107], v[160:163], v[192:195], v[104:107]
	v_mfma_f32_16x16x32_bf16 v[92:95], v[152:155], v[200:203], v[92:95]
	v_mfma_f32_16x16x32_bf16 v[88:91], v[160:163], v[200:203], v[88:91]
	v_mfma_f32_16x16x32_bf16 v[76:79], v[152:155], v[208:211], v[76:79]
	v_mfma_f32_16x16x32_bf16 v[72:75], v[160:163], v[208:211], v[72:75]
	v_mfma_f32_16x16x32_bf16 v[124:127], v[156:159], v[188:191], v[124:127]
	v_mfma_f32_16x16x32_bf16 v[120:123], v[164:167], v[188:191], v[120:123]
	v_mfma_f32_16x16x32_bf16 v[108:111], v[156:159], v[196:199], v[108:111]
	v_mfma_f32_16x16x32_bf16 v[104:107], v[164:167], v[196:199], v[104:107]
	v_mfma_f32_16x16x32_bf16 v[92:95], v[156:159], v[204:207], v[92:95]
	v_mfma_f32_16x16x32_bf16 v[88:91], v[164:167], v[204:207], v[88:91]
	v_mfma_f32_16x16x32_bf16 v[76:79], v[156:159], v[212:215], v[76:79]
	v_mfma_f32_16x16x32_bf16 v[72:75], v[164:167], v[212:215], v[72:75]
	v_mfma_f32_16x16x32_bf16 v[116:119], v[168:171], v[184:187], v[116:119]
	v_mfma_f32_16x16x32_bf16 v[112:115], v[176:179], v[184:187], v[112:115]
	v_mfma_f32_16x16x32_bf16 v[100:103], v[168:171], v[192:195], v[100:103]
	v_mfma_f32_16x16x32_bf16 v[96:99], v[176:179], v[192:195], v[96:99]
	v_mfma_f32_16x16x32_bf16 v[84:87], v[168:171], v[200:203], v[84:87]
	v_mfma_f32_16x16x32_bf16 v[80:83], v[176:179], v[200:203], v[80:83]
	v_mfma_f32_16x16x32_bf16 v[68:71], v[168:171], v[208:211], v[68:71]
	v_mfma_f32_16x16x32_bf16 v[64:67], v[176:179], v[208:211], v[64:67]
	v_mfma_f32_16x16x32_bf16 v[116:119], v[172:175], v[188:191], v[116:119]
	v_mfma_f32_16x16x32_bf16 v[112:115], v[180:183], v[188:191], v[112:115]
	v_mfma_f32_16x16x32_bf16 v[100:103], v[172:175], v[196:199], v[100:103]
	v_mfma_f32_16x16x32_bf16 v[96:99], v[180:183], v[196:199], v[96:99]
	v_mfma_f32_16x16x32_bf16 v[84:87], v[172:175], v[204:207], v[84:87]
	v_mfma_f32_16x16x32_bf16 v[80:83], v[180:183], v[204:207], v[80:83]
	v_mfma_f32_16x16x32_bf16 v[68:71], v[172:175], v[212:215], v[68:71]
	v_mfma_f32_16x16x32_bf16 v[64:67], v[180:183], v[212:215], v[64:67]
	s_barrier
	s_setprio 0
	s_add_i32 s64, s51, s35
	s_mov_b32 m0, s64
	ds_read_b128 v[184:187], v150 offset:16384
	ds_read_b128 v[188:191], v150 offset:17408
	ds_read_b128 v[192:195], v150 offset:18432
	ds_read_b128 v[196:199], v150 offset:19456
	ds_read_b128 v[200:203], v150 offset:20480
	ds_read_b128 v[204:207], v150 offset:21504
	ds_read_b128 v[208:211], v150 offset:22528
	ds_read_b128 v[212:215], v150 offset:23552
	global_load_lds_dwordx4 v130, s[40:41]
	s_add_i32 m0, s64, 0x2000
	s_add_u32 s64, s40, 0x100000
	v_lshl_add_u64 v[218:219], s[40:41], 0, v[134:135]
	s_addc_u32 s65, s41, 0
	s_add_i32 s66, s56, s35
	global_load_lds_dwordx4 v[218:219], off
	s_mov_b32 m0, s66
	s_nop 0
	global_load_lds_dwordx4 v130, s[64:65]
	s_add_i32 m0, s66, 0x2000
	s_nop 0
	global_load_lds_dwordx4 v134, s[64:65]
	s_mov_b32 m0, s44
	s_nop 0
	global_load_lds_dwordx4 v128, s[42:43]
	s_mov_b32 m0, s45
	s_nop 0
	global_load_lds_dwordx4 v132, s[42:43]
	s_waitcnt vmcnt(8)
	s_waitcnt lgkmcnt(0)
	s_setprio 1
	s_barrier
	v_mfma_f32_16x16x32_bf16 v[60:63], v[152:155], v[184:187], v[60:63]
	v_mfma_f32_16x16x32_bf16 v[56:59], v[160:163], v[184:187], v[56:59]
	v_mfma_f32_16x16x32_bf16 v[44:47], v[152:155], v[192:195], v[44:47]
	v_mfma_f32_16x16x32_bf16 v[40:43], v[160:163], v[192:195], v[40:43]
	v_mfma_f32_16x16x32_bf16 v[28:31], v[152:155], v[200:203], v[28:31]
	v_mfma_f32_16x16x32_bf16 v[24:27], v[160:163], v[200:203], v[24:27]
	v_mfma_f32_16x16x32_bf16 v[12:15], v[152:155], v[208:211], v[12:15]
	v_mfma_f32_16x16x32_bf16 v[8:11], v[160:163], v[208:211], v[8:11]
	v_mfma_f32_16x16x32_bf16 v[60:63], v[156:159], v[188:191], v[60:63]
	v_mfma_f32_16x16x32_bf16 v[56:59], v[164:167], v[188:191], v[56:59]
	v_mfma_f32_16x16x32_bf16 v[44:47], v[156:159], v[196:199], v[44:47]
	v_mfma_f32_16x16x32_bf16 v[40:43], v[164:167], v[196:199], v[40:43]
	v_mfma_f32_16x16x32_bf16 v[28:31], v[156:159], v[204:207], v[28:31]
	v_mfma_f32_16x16x32_bf16 v[24:27], v[164:167], v[204:207], v[24:27]
	v_mfma_f32_16x16x32_bf16 v[12:15], v[156:159], v[212:215], v[12:15]
	v_mfma_f32_16x16x32_bf16 v[8:11], v[164:167], v[212:215], v[8:11]
	v_mfma_f32_16x16x32_bf16 v[52:55], v[168:171], v[184:187], v[52:55]
	v_mfma_f32_16x16x32_bf16 v[48:51], v[176:179], v[184:187], v[48:51]
	v_mfma_f32_16x16x32_bf16 v[36:39], v[168:171], v[192:195], v[36:39]
	v_mfma_f32_16x16x32_bf16 v[32:35], v[176:179], v[192:195], v[32:35]
	v_mfma_f32_16x16x32_bf16 v[20:23], v[168:171], v[200:203], v[20:23]
	v_mfma_f32_16x16x32_bf16 v[16:19], v[176:179], v[200:203], v[16:19]
	v_mfma_f32_16x16x32_bf16 v[4:7], v[168:171], v[208:211], v[4:7]
	v_mfma_f32_16x16x32_bf16 v[0:3], v[176:179], v[208:211], v[0:3]
	v_mfma_f32_16x16x32_bf16 v[52:55], v[172:175], v[188:191], v[52:55]
	v_mfma_f32_16x16x32_bf16 v[48:51], v[180:183], v[188:191], v[48:51]
	v_mfma_f32_16x16x32_bf16 v[36:39], v[172:175], v[196:199], v[36:39]
	v_mfma_f32_16x16x32_bf16 v[32:35], v[180:183], v[196:199], v[32:35]
	v_mfma_f32_16x16x32_bf16 v[20:23], v[172:175], v[204:207], v[20:23]
	v_mfma_f32_16x16x32_bf16 v[16:19], v[180:183], v[204:207], v[16:19]
	v_mfma_f32_16x16x32_bf16 v[4:7], v[172:175], v[212:215], v[4:7]
	v_mfma_f32_16x16x32_bf16 v[0:3], v[180:183], v[212:215], v[0:3]
	s_barrier
	s_setprio 0
	s_add_i32 s64, 0, 0x18000
	v_add_u32_e32 v151, s64, v149
	s_add_i32 s65, 0, 0x1c000
	ds_read_b128 v[152:155], v151
	ds_read_b128 v[156:159], v151 offset:1024
	ds_read_b128 v[160:163], v151 offset:2048
	ds_read_b128 v[164:167], v151 offset:3072
	v_add_u32_e32 v151, s65, v149
	ds_read_b128 v[168:171], v151
	ds_read_b128 v[172:175], v151 offset:1024
	ds_read_b128 v[176:179], v151 offset:2048
	ds_read_b128 v[180:183], v151 offset:3072
	s_add_u32 s42, s42, 0x2000
	s_addc_u32 s43, s43, 0
	s_mov_b32 m0, s46
	ds_read_b128 v[184:187], v150 offset:32768
	ds_read_b128 v[188:191], v150 offset:33792
	ds_read_b128 v[192:195], v150 offset:34816
	ds_read_b128 v[196:199], v150 offset:35840
	ds_read_b128 v[200:203], v150 offset:36864
	ds_read_b128 v[204:207], v150 offset:37888
	ds_read_b128 v[208:211], v150 offset:38912
	ds_read_b128 v[212:215], v150 offset:39936
	global_load_lds_dwordx4 v128, s[42:43]
	s_mov_b32 m0, s47
	s_nop 0
	global_load_lds_dwordx4 v132, s[42:43]
	s_waitcnt vmcnt(8)
	s_waitcnt lgkmcnt(0)
	s_setprio 1
	s_barrier
	v_mfma_f32_16x16x32_bf16 v[124:127], v[152:155], v[184:187], v[124:127]
	v_mfma_f32_16x16x32_bf16 v[120:123], v[160:163], v[184:187], v[120:123]
	v_mfma_f32_16x16x32_bf16 v[108:111], v[152:155], v[192:195], v[108:111]
	v_mfma_f32_16x16x32_bf16 v[104:107], v[160:163], v[192:195], v[104:107]
	v_mfma_f32_16x16x32_bf16 v[92:95], v[152:155], v[200:203], v[92:95]
	v_mfma_f32_16x16x32_bf16 v[88:91], v[160:163], v[200:203], v[88:91]
	v_mfma_f32_16x16x32_bf16 v[76:79], v[152:155], v[208:211], v[76:79]
	v_mfma_f32_16x16x32_bf16 v[72:75], v[160:163], v[208:211], v[72:75]
	v_mfma_f32_16x16x32_bf16 v[124:127], v[156:159], v[188:191], v[124:127]
	v_mfma_f32_16x16x32_bf16 v[120:123], v[164:167], v[188:191], v[120:123]
	v_mfma_f32_16x16x32_bf16 v[108:111], v[156:159], v[196:199], v[108:111]
	v_mfma_f32_16x16x32_bf16 v[104:107], v[164:167], v[196:199], v[104:107]
	v_mfma_f32_16x16x32_bf16 v[92:95], v[156:159], v[204:207], v[92:95]
	v_mfma_f32_16x16x32_bf16 v[88:91], v[164:167], v[204:207], v[88:91]
	v_mfma_f32_16x16x32_bf16 v[76:79], v[156:159], v[212:215], v[76:79]
	v_mfma_f32_16x16x32_bf16 v[72:75], v[164:167], v[212:215], v[72:75]
	v_mfma_f32_16x16x32_bf16 v[116:119], v[168:171], v[184:187], v[116:119]
	v_mfma_f32_16x16x32_bf16 v[112:115], v[176:179], v[184:187], v[112:115]
	v_mfma_f32_16x16x32_bf16 v[100:103], v[168:171], v[192:195], v[100:103]
	v_mfma_f32_16x16x32_bf16 v[96:99], v[176:179], v[192:195], v[96:99]
	v_mfma_f32_16x16x32_bf16 v[84:87], v[168:171], v[200:203], v[84:87]
	v_mfma_f32_16x16x32_bf16 v[80:83], v[176:179], v[200:203], v[80:83]
	v_mfma_f32_16x16x32_bf16 v[68:71], v[168:171], v[208:211], v[68:71]
	v_mfma_f32_16x16x32_bf16 v[64:67], v[176:179], v[208:211], v[64:67]
	v_mfma_f32_16x16x32_bf16 v[116:119], v[172:175], v[188:191], v[116:119]
	v_mfma_f32_16x16x32_bf16 v[112:115], v[180:183], v[188:191], v[112:115]
	v_mfma_f32_16x16x32_bf16 v[100:103], v[172:175], v[196:199], v[100:103]
	v_mfma_f32_16x16x32_bf16 v[96:99], v[180:183], v[196:199], v[96:99]
	v_mfma_f32_16x16x32_bf16 v[84:87], v[172:175], v[204:207], v[84:87]
	v_mfma_f32_16x16x32_bf16 v[80:83], v[180:183], v[204:207], v[80:83]
	v_mfma_f32_16x16x32_bf16 v[68:71], v[172:175], v[212:215], v[68:71]
	v_mfma_f32_16x16x32_bf16 v[64:67], v[180:183], v[212:215], v[64:67]
	s_barrier
	s_setprio 0
	s_add_u32 s98, s40, s16
	s_addc_u32 s99, s41, s17
	s_add_i32 s42, s64, s35
	s_mov_b32 m0, s42
	ds_read_b128 v[184:187], v150 offset:49152
	ds_read_b128 v[188:191], v150 offset:50176
	ds_read_b128 v[192:195], v150 offset:51200
	ds_read_b128 v[196:199], v150 offset:52224
	ds_read_b128 v[200:203], v150 offset:53248
	ds_read_b128 v[204:207], v150 offset:54272
	ds_read_b128 v[208:211], v150 offset:55296
	ds_read_b128 v[212:215], v150 offset:56320
	global_load_lds_dwordx4 v130, s[98:99]
	s_add_i32 m0, s42, 0x2000
	s_add_u32 s40, s40, 0x100080
	v_lshl_add_u64 v[216:217], v[218:219], 0, s[16:17]
	s_addc_u32 s41, s41, 0
	s_add_i32 s42, s65, s35
	global_load_lds_dwordx4 v[216:217], off
	s_mov_b32 m0, s42
	s_nop 0
	global_load_lds_dwordx4 v130, s[40:41]
	s_add_i32 m0, s42, 0x2000
	s_nop 0
	global_load_lds_dwordx4 v134, s[40:41]
	s_mov_b32 m0, s48
	s_nop 0
	global_load_lds_dwordx4 v128, s[38:39]
	s_mov_b32 m0, s49
	s_nop 0
	global_load_lds_dwordx4 v132, s[38:39]
	s_waitcnt vmcnt(8)
	s_waitcnt lgkmcnt(0)
	s_setprio 1
	s_barrier
	v_mfma_f32_16x16x32_bf16 v[60:63], v[152:155], v[184:187], v[60:63]
	v_mfma_f32_16x16x32_bf16 v[56:59], v[160:163], v[184:187], v[56:59]
	v_mfma_f32_16x16x32_bf16 v[44:47], v[152:155], v[192:195], v[44:47]
	v_mfma_f32_16x16x32_bf16 v[40:43], v[160:163], v[192:195], v[40:43]
	v_mfma_f32_16x16x32_bf16 v[28:31], v[152:155], v[200:203], v[28:31]
	v_mfma_f32_16x16x32_bf16 v[24:27], v[160:163], v[200:203], v[24:27]
	v_mfma_f32_16x16x32_bf16 v[12:15], v[152:155], v[208:211], v[12:15]
	v_mfma_f32_16x16x32_bf16 v[8:11], v[160:163], v[208:211], v[8:11]
	v_mfma_f32_16x16x32_bf16 v[60:63], v[156:159], v[188:191], v[60:63]
	v_mfma_f32_16x16x32_bf16 v[56:59], v[164:167], v[188:191], v[56:59]
	v_mfma_f32_16x16x32_bf16 v[44:47], v[156:159], v[196:199], v[44:47]
	v_mfma_f32_16x16x32_bf16 v[40:43], v[164:167], v[196:199], v[40:43]
	v_mfma_f32_16x16x32_bf16 v[28:31], v[156:159], v[204:207], v[28:31]
	v_mfma_f32_16x16x32_bf16 v[24:27], v[164:167], v[204:207], v[24:27]
	v_mfma_f32_16x16x32_bf16 v[12:15], v[156:159], v[212:215], v[12:15]
	v_mfma_f32_16x16x32_bf16 v[8:11], v[164:167], v[212:215], v[8:11]
	v_mfma_f32_16x16x32_bf16 v[52:55], v[168:171], v[184:187], v[52:55]
	v_mfma_f32_16x16x32_bf16 v[48:51], v[176:179], v[184:187], v[48:51]
	v_mfma_f32_16x16x32_bf16 v[36:39], v[168:171], v[192:195], v[36:39]
	v_mfma_f32_16x16x32_bf16 v[32:35], v[176:179], v[192:195], v[32:35]
	v_mfma_f32_16x16x32_bf16 v[20:23], v[168:171], v[200:203], v[20:23]
	v_mfma_f32_16x16x32_bf16 v[16:19], v[176:179], v[200:203], v[16:19]
	v_mfma_f32_16x16x32_bf16 v[4:7], v[168:171], v[208:211], v[4:7]
	v_mfma_f32_16x16x32_bf16 v[0:3], v[176:179], v[208:211], v[0:3]
	v_mfma_f32_16x16x32_bf16 v[52:55], v[172:175], v[188:191], v[52:55]
	v_mfma_f32_16x16x32_bf16 v[48:51], v[180:183], v[188:191], v[48:51]
	v_mfma_f32_16x16x32_bf16 v[36:39], v[172:175], v[196:199], v[36:39]
	v_mfma_f32_16x16x32_bf16 v[32:35], v[180:183], v[196:199], v[32:35]
	v_mfma_f32_16x16x32_bf16 v[20:23], v[172:175], v[204:207], v[20:23]
	v_mfma_f32_16x16x32_bf16 v[16:19], v[180:183], v[204:207], v[16:19]
	v_mfma_f32_16x16x32_bf16 v[4:7], v[172:175], v[212:215], v[4:7]
	v_mfma_f32_16x16x32_bf16 v[0:3], v[180:183], v[212:215], v[0:3]
	s_barrier
	s_setprio 0
	s_add_i32 s63, s63, 2
	s_add_u32 s61, s61, 0x100
	s_addc_u32 s62, s62, 0
	s_add_u32 s36, s36, 0x10000
	s_addc_u32 s37, s37, 0
	v_lshl_add_u64 v[146:147], v[146:147], 0, s[18:19]
	s_cmp_gt_u32 s63, 61
	v_lshl_add_u64 v[144:145], v[144:145], 0, s[18:19]
	s_cbranch_scc0 .LBB0_615
	s_andn2_b64 vcc, exec, s[4:5]
	s_cbranch_vccnz .LBB0_607
	s_mov_b32 s8, s20
	s_mov_b32 s6, s22
	s_mov_b64 s[10:11], s[28:29]
	s_mov_b64 s[12:13], s[26:27]
	s_mov_b32 s50, s57
	v_mov_b64_e32 v[0:1], 0
	v_mov_b64_e32 v[2:3], 0
	v_mov_b64_e32 v[4:5], 0
	v_mov_b64_e32 v[6:7], 0
	v_mov_b64_e32 v[8:9], 0
	v_mov_b64_e32 v[10:11], 0
	v_mov_b64_e32 v[12:13], 0
	v_mov_b64_e32 v[14:15], 0
	v_mov_b64_e32 v[16:17], 0
	v_mov_b64_e32 v[18:19], 0
	v_mov_b64_e32 v[20:21], 0
	v_mov_b64_e32 v[22:23], 0
	v_mov_b64_e32 v[24:25], 0
	v_mov_b64_e32 v[26:27], 0
	v_mov_b64_e32 v[28:29], 0
	v_mov_b64_e32 v[30:31], 0
	v_mov_b64_e32 v[32:33], 0
	v_mov_b64_e32 v[34:35], 0
	v_mov_b64_e32 v[36:37], 0
	v_mov_b64_e32 v[38:39], 0
	v_mov_b64_e32 v[40:41], 0
	v_mov_b64_e32 v[42:43], 0
	v_mov_b64_e32 v[44:45], 0
	v_mov_b64_e32 v[46:47], 0
	v_mov_b64_e32 v[48:49], 0
	v_mov_b64_e32 v[50:51], 0
	v_mov_b64_e32 v[52:53], 0
	v_mov_b64_e32 v[54:55], 0
	v_mov_b64_e32 v[56:57], 0
	v_mov_b64_e32 v[58:59], 0
	v_mov_b64_e32 v[60:61], 0
	v_mov_b64_e32 v[62:63], 0
	v_mov_b64_e32 v[64:65], 0
	v_mov_b64_e32 v[66:67], 0
	v_mov_b64_e32 v[68:69], 0
	v_mov_b64_e32 v[70:71], 0
	v_mov_b64_e32 v[72:73], 0
	v_mov_b64_e32 v[74:75], 0
	v_mov_b64_e32 v[76:77], 0
	v_mov_b64_e32 v[78:79], 0
	v_mov_b64_e32 v[80:81], 0
	v_mov_b64_e32 v[82:83], 0
	v_mov_b64_e32 v[84:85], 0
	v_mov_b64_e32 v[86:87], 0
	v_mov_b64_e32 v[88:89], 0
	v_mov_b64_e32 v[90:91], 0
	v_mov_b64_e32 v[92:93], 0
	v_mov_b64_e32 v[94:95], 0
	v_mov_b64_e32 v[96:97], 0
	v_mov_b64_e32 v[98:99], 0
	v_mov_b64_e32 v[100:101], 0
	v_mov_b64_e32 v[102:103], 0
	v_mov_b64_e32 v[104:105], 0
	v_mov_b64_e32 v[106:107], 0
	v_mov_b64_e32 v[108:109], 0
	v_mov_b64_e32 v[110:111], 0
	v_mov_b64_e32 v[112:113], 0
	v_mov_b64_e32 v[114:115], 0
	v_mov_b64_e32 v[116:117], 0
	v_mov_b64_e32 v[118:119], 0
	v_mov_b64_e32 v[120:121], 0
	v_mov_b64_e32 v[122:123], 0
	v_mov_b64_e32 v[124:125], 0
	v_mov_b64_e32 v[126:127], 0
	s_branch .LBB0_607
